# phase-5 second workgroup per CU walks items in reverse order; phase-2 V^T (kind 3) tiles stored via wave-private LDS transpose
# speedup vs baseline: 1.0145x; 1.0007x over previous
.Lp2_trans_setup:
	s_lshl_b32 s34, s30, 1
	s_add_u32 s34, s34, s13
	s_lshl_b32 s34, s34, 20
	s_lshl_b32 s35, s31, 1
	s_add_u32 s34, s34, s35
	s_add_u32 s33, s33, s34
	s_add_u32 s40, s88, s33
	s_addc_u32 s41, s89, 0
	s_nop 15
	s_lshl_b32 s14, s12, 1
	s_add_u32 s40, s40, s14
	s_addc_u32 s41, s41, 0
	v_readfirstlane_b32 s30, v186
	s_lshr_b32 s30, s30, 6
	s_mul_i32 s30, s30, 0x2400
	v_and_b32_e32 v100, 31, v186
	v_bfe_u32 v101, v186, 5, 1
	v_mul_u32_u24_e32 v101, 576, v101
	v_lshl_add_u32 v100, v100, 1, v101
	v_add_u32_e32 v100, s30, v100
	v_and_b32_e32 v102, 63, v186
	v_lshrrev_b32_e32 v103, 3, v102
	v_and_b32_e32 v102, 7, v102
	v_mul_u32_u24_e32 v104, 144, v103
	v_lshl_add_u32 v104, v102, 4, v104
	v_add_u32_e32 v104, s30, v104
	v_mul_u32_u24_e32 v105, 16384, v103
	v_lshl_add_u32 v105, v102, 4, v105
	v_cvt_pk_bf16_f32 v106, v48, v49
	ds_write_b16 v100, v106
	ds_write_b16_d16_hi v100, v106 offset:144
	v_cvt_pk_bf16_f32 v107, v50, v51
	ds_write_b16 v100, v107 offset:288
	ds_write_b16_d16_hi v100, v107 offset:432
	v_cvt_pk_bf16_f32 v108, v52, v53
	ds_write_b16 v100, v108 offset:1152
	ds_write_b16_d16_hi v100, v108 offset:1296
	v_cvt_pk_bf16_f32 v109, v54, v55
	ds_write_b16 v100, v109 offset:1440
	ds_write_b16_d16_hi v100, v109 offset:1584
	v_cvt_pk_bf16_f32 v110, v56, v57
	ds_write_b16 v100, v110 offset:2304
	ds_write_b16_d16_hi v100, v110 offset:2448
	v_cvt_pk_bf16_f32 v111, v58, v59
	ds_write_b16 v100, v111 offset:2592
	ds_write_b16_d16_hi v100, v111 offset:2736
	v_cvt_pk_bf16_f32 v112, v60, v61
	ds_write_b16 v100, v112 offset:3456
	ds_write_b16_d16_hi v100, v112 offset:3600
	v_cvt_pk_bf16_f32 v113, v62, v63
	ds_write_b16 v100, v113 offset:3744
	ds_write_b16_d16_hi v100, v113 offset:3888
	v_cvt_pk_bf16_f32 v114, v16, v17
	ds_write_b16 v100, v114 offset:64
	ds_write_b16_d16_hi v100, v114 offset:208
	v_cvt_pk_bf16_f32 v115, v18, v19
	ds_write_b16 v100, v115 offset:352
	ds_write_b16_d16_hi v100, v115 offset:496
	v_cvt_pk_bf16_f32 v116, v20, v21
	ds_write_b16 v100, v116 offset:1216
	ds_write_b16_d16_hi v100, v116 offset:1360
	v_cvt_pk_bf16_f32 v117, v22, v23
	ds_write_b16 v100, v117 offset:1504
	ds_write_b16_d16_hi v100, v117 offset:1648
	v_cvt_pk_bf16_f32 v118, v24, v25
	ds_write_b16 v100, v118 offset:2368
	ds_write_b16_d16_hi v100, v118 offset:2512
	v_cvt_pk_bf16_f32 v119, v26, v27
	ds_write_b16 v100, v119 offset:2656
	ds_write_b16_d16_hi v100, v119 offset:2800
	v_cvt_pk_bf16_f32 v120, v28, v29
	ds_write_b16 v100, v120 offset:3520
	ds_write_b16_d16_hi v100, v120 offset:3664
	v_cvt_pk_bf16_f32 v121, v30, v31
	ds_write_b16 v100, v121 offset:3808
	ds_write_b16_d16_hi v100, v121 offset:3952
	v_cvt_pk_bf16_f32 v122, v32, v33
	ds_write_b16 v100, v122 offset:4608
	ds_write_b16_d16_hi v100, v122 offset:4752
	v_cvt_pk_bf16_f32 v123, v34, v35
	ds_write_b16 v100, v123 offset:4896
	ds_write_b16_d16_hi v100, v123 offset:5040
	v_cvt_pk_bf16_f32 v124, v36, v37
	ds_write_b16 v100, v124 offset:5760
	ds_write_b16_d16_hi v100, v124 offset:5904
	v_cvt_pk_bf16_f32 v125, v38, v39
	ds_write_b16 v100, v125 offset:6048
	ds_write_b16_d16_hi v100, v125 offset:6192
	v_cvt_pk_bf16_f32 v126, v40, v41
	ds_write_b16 v100, v126 offset:6912
	ds_write_b16_d16_hi v100, v126 offset:7056
	v_cvt_pk_bf16_f32 v127, v42, v43
	ds_write_b16 v100, v127 offset:7200
	ds_write_b16_d16_hi v100, v127 offset:7344
	v_cvt_pk_bf16_f32 v128, v44, v45
	ds_write_b16 v100, v128 offset:8064
	ds_write_b16_d16_hi v100, v128 offset:8208
	v_cvt_pk_bf16_f32 v129, v46, v47
	ds_write_b16 v100, v129 offset:8352
	ds_write_b16_d16_hi v100, v129 offset:8496
	v_cvt_pk_bf16_f32 v130, v0, v1
	ds_write_b16 v100, v130 offset:4672
	ds_write_b16_d16_hi v100, v130 offset:4816
	v_cvt_pk_bf16_f32 v131, v2, v3
	ds_write_b16 v100, v131 offset:4960
	ds_write_b16_d16_hi v100, v131 offset:5104
	v_cvt_pk_bf16_f32 v132, v4, v5
	ds_write_b16 v100, v132 offset:5824
	ds_write_b16_d16_hi v100, v132 offset:5968
	v_cvt_pk_bf16_f32 v133, v6, v7
	ds_write_b16 v100, v133 offset:6112
	ds_write_b16_d16_hi v100, v133 offset:6256
	v_cvt_pk_bf16_f32 v134, v8, v9
	ds_write_b16 v100, v134 offset:6976
	ds_write_b16_d16_hi v100, v134 offset:7120
	v_cvt_pk_bf16_f32 v135, v10, v11
	ds_write_b16 v100, v135 offset:7264
	ds_write_b16_d16_hi v100, v135 offset:7408
	v_cvt_pk_bf16_f32 v136, v12, v13
	ds_write_b16 v100, v136 offset:8128
	ds_write_b16_d16_hi v100, v136 offset:8272
	v_cvt_pk_bf16_f32 v137, v14, v15
	ds_write_b16 v100, v137 offset:8416
	ds_write_b16_d16_hi v100, v137 offset:8560
	s_waitcnt lgkmcnt(0)
	ds_read_b128 v[106:109], v104
	ds_read_b128 v[110:113], v104 offset:1152
	ds_read_b128 v[114:117], v104 offset:2304
	ds_read_b128 v[118:121], v104 offset:3456
	ds_read_b128 v[122:125], v104 offset:4608
	ds_read_b128 v[126:129], v104 offset:5760
	ds_read_b128 v[130:133], v104 offset:6912
	ds_read_b128 v[134:137], v104 offset:8064
	s_waitcnt lgkmcnt(7)
	global_store_dwordx4 v105, v[106:109], s[40:41]
	s_add_u32 s40, s40, 131072
	s_addc_u32 s41, s41, 0
	s_waitcnt lgkmcnt(6)
	global_store_dwordx4 v105, v[110:113], s[40:41]
	s_add_u32 s40, s40, 131072
	s_addc_u32 s41, s41, 0
	s_waitcnt lgkmcnt(5)
	global_store_dwordx4 v105, v[114:117], s[40:41]
	s_add_u32 s40, s40, 131072
	s_addc_u32 s41, s41, 0
	s_waitcnt lgkmcnt(4)
	global_store_dwordx4 v105, v[118:121], s[40:41]
	s_add_u32 s40, s40, 131072
	s_addc_u32 s41, s41, 0
	s_waitcnt lgkmcnt(3)
	global_store_dwordx4 v105, v[122:125], s[40:41]
	s_add_u32 s40, s40, 131072
	s_addc_u32 s41, s41, 0
	s_waitcnt lgkmcnt(2)
	global_store_dwordx4 v105, v[126:129], s[40:41]
	s_add_u32 s40, s40, 131072
	s_addc_u32 s41, s41, 0
	s_waitcnt lgkmcnt(1)
	global_store_dwordx4 v105, v[130:133], s[40:41]
	s_add_u32 s40, s40, 131072
	s_addc_u32 s41, s41, 0
	s_waitcnt lgkmcnt(0)
	global_store_dwordx4 v105, v[134:137], s[40:41]
	s_movk_i32 s34, 0x3fff
	s_branch .LBB0_341

.LBB0_1890:
	s_or_b64 exec, exec, s[0:1]
	s_mov_b64 s[0:1], s[88:89]
	s_waitcnt lgkmcnt(0)
	v_mov_b32_e32 v0, v186
	s_mov_b32 s2, s90
	s_barrier
	s_nop 0
	v_readlane_b32 s2, v252, 34
	v_readlane_b32 s3, v252, 35
	s_andn2_b64 vcc, exec, s[2:3]
	s_cbranch_vccnz .LBB0_2024
	v_mov_b32_e32 v220, v186
	v_ashrrev_i32_e32 v221, 31, v220
	v_lshrrev_b32_e32 v222, 29, v221
	v_add_u32_e32 v223, v220, v222
	v_ashrrev_i32_e32 v224, 3, v223
	v_and_b32_e32 v225, 0xffffff8, v223
	v_lshlrev_b32_e32 v226, 2, v224
	v_lshrrev_b32_e32 v227, 1, v224
	v_sub_u32_e32 v228, v220, v225
	v_and_b32_e32 v229, 16, v226
	v_and_b32_e32 v230, 12, v227
	v_and_b32_e32 v231, 35, v224
	v_or3_b32 v232, v231, v229, v230
	v_lshlrev_b32_e32 v233, 4, v228
	v_mad_u32_u24 v234, v232, s43, v233
	v_mov_b32_e32 v214, v234
	v_mov_b32_e32 v220, v186
	v_lshlrev_b32_e32 v221, 4, v220
	v_and_b32_e32 v222, 0x70, v221
	v_lshrrev_b32_e32 v223, 3, v220
	v_mad_u64_u32 v[224:225], vcc, v223, s43, v[222:223]
	v_mov_b32_e32 v218, v224
	v_mov_b32_e32 v220, v186
	v_mul_hi_i32 v221, v220, s91
	v_lshrrev_b32_e32 v222, 31, v221
	v_ashrrev_i32_e32 v223, 1, v221
	v_add_u32_e32 v224, v223, v222
	v_mul_lo_u32 v225, v224, 12
	v_lshlrev_b32_e32 v226, 2, v224
	v_lshrrev_b32_e32 v227, 1, v224
	v_sub_u32_e32 v228, v220, v225
	v_and_b32_e32 v229, 16, v226
	v_and_b32_e32 v230, 12, v227
	v_and_b32_e32 v231, 35, v224
	v_or3_b32 v232, v231, v229, v230
	v_lshlrev_b32_e32 v233, 4, v228
	v_mad_u32_u24 v234, v232, s36, v233
	v_mov_b32_e32 v215, v234
	v_mov_b32_e32 v220, v186
	v_add_u32_e32 v221, 0x100, v220
	v_mul_hi_i32 v222, v221, s91
	v_lshrrev_b32_e32 v223, 31, v222
	v_ashrrev_i32_e32 v224, 1, v222
	v_add_u32_e32 v225, v224, v223
	v_mul_lo_u32 v226, v225, 12
	v_lshlrev_b32_e32 v227, 2, v225
	v_lshrrev_b32_e32 v228, 1, v225
	v_sub_u32_e32 v229, v221, v226
	v_and_b32_e32 v230, 16, v227
	v_and_b32_e32 v231, 12, v228
	v_and_b32_e32 v232, 35, v225
	v_or3_b32 v233, v232, v230, v231
	v_lshlrev_b32_e32 v234, 4, v229
	v_mad_u32_u24 v235, v233, s36, v234
	v_mov_b32_e32 v216, v235
	v_mov_b32_e32 v220, v186
	v_add_u32_e32 v221, 0x200, v220
	v_mul_hi_i32 v222, v221, s91
	v_lshrrev_b32_e32 v223, 31, v222
	v_ashrrev_i32_e32 v224, 1, v222
	v_add_u32_e32 v225, v224, v223
	v_mul_lo_u32 v226, v225, 12
	v_sub_u32_e32 v227, v221, v226
	v_lshlrev_b32_e32 v228, 2, v225
	v_lshrrev_b32_e32 v229, 1, v225
	v_and_b32_e32 v230, 16, v228
	v_and_b32_e32 v231, 12, v229
	v_and_b32_e32 v232, 35, v225
	v_or3_b32 v233, v232, v230, v231
	v_lshlrev_b32_e32 v234, 4, v227
	v_mad_u32_u24 v235, v233, s36, v234
	v_mov_b32_e32 v217, v235
	v_and_b32_e32 v246, 15, v186
	v_and_b32_e32 v247, 48, v186
	v_mad_u32_u24 v245, v246, s43, v247
	v_mad_u32_u24 v244, v246, s36, v247
	v_bfe_u32 v248, v186, 4, 2
	v_lshlrev_b32_e32 v248, 3, v248
	v_lshlrev_b32_e32 v219, 4, v186
	v_add_u32_e32 v236, 0x1000, v219
	v_add_u32_e32 v241, 0x2000, v219
	v_and_b32_e32 v220, 0x70, v219
	v_lshrrev_b32_e32 v221, 3, v186
	v_lshl_or_b32 v237, v221, 14, v220
	v_add_u32_e32 v238, 0x80000, v237
	v_lshl_or_b32 v239, v221, 10, v220
	v_add_u32_e32 v240, 0x8000, v239
	s_add_u32 s2, s0, 0x7000000
	s_addc_u32 s3, s1, 0
	v_writelane_b32 v254, s2, 36
	s_nop 1
	v_writelane_b32 v254, s3, 37
	s_add_u32 s2, s0, 0x8000000
	v_writelane_b32 v254, s2, 38
	s_addc_u32 s2, s1, 0
	v_writelane_b32 v254, s2, 39
	s_lshl_b32 s2, s22, 3
	s_mov_b32 s3, s77
	s_lshl_b64 s[2:3], s[2:3], 2
	s_add_u32 s2, s58, s2
	s_addc_u32 s3, s59, s3
	v_writelane_b32 v254, s2, 40
	s_nop 1
	v_writelane_b32 v254, s3, 41
	s_add_u32 s2, s0, 0x8400000
	v_writelane_b32 v254, s2, 42
	s_addc_u32 s2, s1, 0
	v_writelane_b32 v254, s2, 43
	s_add_u32 s2, s0, 0x4800000
	s_addc_u32 s3, s1, 0
	v_writelane_b32 v254, s2, 30
	s_nop 1
	v_writelane_b32 v254, s3, 31
	s_add_u32 s2, s0, 0x6400000
	v_writelane_b32 v254, s2, 44
	s_addc_u32 s2, s1, 0
	v_writelane_b32 v254, s2, 45
	s_add_u32 s2, s0, 0x6c00000
	v_writelane_b32 v254, s2, 46
	s_addc_u32 s2, s1, 0
	v_writelane_b32 v254, s2, 47
	s_add_u32 s2, s0, 0xe200000
	v_writelane_b32 v254, s2, 48
	s_addc_u32 s2, s1, 0
	v_writelane_b32 v254, s2, 49
	s_add_u32 s2, s0, 0x6000000
	v_writelane_b32 v254, s2, 50
	s_addc_u32 s2, s1, 0
	v_writelane_b32 v254, s2, 51
	s_add_u32 s2, s0, 0x6800000
	v_writelane_b32 v254, s2, 52
	s_addc_u32 s2, s1, 0
	v_writelane_b32 v254, s2, 53
	s_add_u32 s2, s0, 0x9800000
	s_addc_u32 s3, s1, 0
	v_writelane_b32 v254, s2, 54
	s_nop 1
	v_writelane_b32 v254, s3, 55
	s_add_u32 s2, s0, 0xe240000
	v_writelane_b32 v254, s2, 56
	s_addc_u32 s2, s1, 0
	v_writelane_b32 v254, s2, 57
	s_add_u32 s2, s0, 0x9a00000
	s_addc_u32 s3, s1, 0
	v_writelane_b32 v254, s2, 58
	s_nop 1
	v_writelane_b32 v254, s3, 59
	s_add_u32 s2, s0, 0xca00000
	v_writelane_b32 v254, s2, 60
	s_addc_u32 s2, s1, 0
	v_writelane_b32 v254, s2, 61
	s_add_u32 s2, s0, 0xb200000
	v_writelane_b32 v254, s2, 62
	s_addc_u32 s2, s1, 0
	v_writelane_b32 v254, s2, 63
	s_add_u32 s2, s0, 0x8800000
	v_writelane_b32 v255, s2, 0
	s_addc_u32 s2, s1, 0
	v_writelane_b32 v255, s2, 1
	s_add_u32 s2, s0, 0x8002000
	s_addc_u32 s3, s1, 0
	v_writelane_b32 v255, s2, 2
	v_readlane_b32 s41, v254, 16
	v_readlane_b32 s96, v254, 17
	v_writelane_b32 v255, s3, 3
	s_add_u32 s2, s0, 0xe202000
	v_writelane_b32 v255, s2, 4
	s_addc_u32 s2, s1, 0
	v_writelane_b32 v255, s2, 5
	s_add_u32 s2, s0, 0xe240080
	v_writelane_b32 v255, s2, 6
	s_addc_u32 s2, s1, 0
	v_writelane_b32 v255, s2, 7
	s_add_u32 s2, s0, 0x6802000
	v_writelane_b32 v255, s2, 8
	s_addc_u32 s2, s1, 0
	v_writelane_b32 v255, s2, 9
	s_add_u32 s0, s0, 0xb209000
	v_writelane_b32 v255, s0, 10
	s_addc_u32 s0, s1, 0
	v_writelane_b32 v255, s0, 11
	s_mov_b32 s80, s41
	s_mov_b32 s81, s41
	v_readlane_b32 s97, v254, 18
	v_readlane_b32 s40, v254, 14
	s_cmpk_lg_i32 s90, 0x200
	s_cbranch_scc1 .Lp5_fwd
	v_readlane_b32 s2, v251, 47
	s_nop 1
	s_cmp_lt_u32 s2, 0x400
	s_cbranch_scc1 .Lp5_fwd
	s_addk_i32 s41, 0xa00
	s_mov_b32 s80, s41
	s_mov_b32 s81, s41
	v_readlane_b32 s2, v254, 15
	s_nop 1
	s_mul_i32 s2, s2, 5
	s_add_i32 s40, s40, s2
.Lp5_fwd:
	s_branch .LBB0_1894
.LBB0_1892:
	v_mov_b32_e32 v0, v134
	s_nop 1
	v_permlane16_swap_b32_e32 v134, v0
	v_add_f32_e32 v1, v134, v0
	v_mov_b32_e32 v0, v135
	s_nop 1
	v_permlane16_swap_b32_e32 v135, v0
	v_add_f32_e32 v0, v135, v0
	v_mov_b32_e32 v3, v1
	v_mov_b32_e32 v2, v0
	s_nop 0
	v_permlane32_swap_b32_e32 v1, v3
	v_permlane32_swap_b32_e32 v0, v2
	v_pk_add_f32 v[0:1], v[0:1], v[2:3]
	v_lshlrev_b32_e32 v160, 3, v138
	v_div_scale_f32 v2, s[0:1], v1, v1, 1.0
	v_rcp_f32_e32 v3, v2
	s_nop 0
	v_fma_f32 v4, -v2, v3, 1.0
	v_fmac_f32_e32 v3, v4, v3
	v_div_scale_f32 v4, vcc, 1.0, v1, 1.0
	v_mul_f32_e32 v5, v4, v3
	v_fma_f32 v6, -v2, v5, v4
	v_fmac_f32_e32 v5, v6, v3
	v_fma_f32 v2, -v2, v5, v4
	v_div_fmas_f32 v2, v2, v3, v5
	v_div_scale_f32 v3, s[0:1], v0, v0, 1.0
	v_rcp_f32_e32 v4, v3
	v_div_fixup_f32 v2, v2, v1, 1.0
	v_cmp_lt_f32_e32 vcc, 0, v1
	s_lshl_b32 s0, s12, 7
	v_fma_f32 v1, -v3, v4, 1.0
	v_cndmask_b32_e32 v2, 0, v2, vcc
	v_fmac_f32_e32 v4, v1, v4
	v_div_scale_f32 v1, vcc, 1.0, v0, 1.0
	v_mul_f32_e32 v5, v1, v4
	v_fma_f32 v6, -v3, v5, v1
	v_readlane_b32 s1, v255, 0
	v_fmac_f32_e32 v5, v6, v4
	s_add_u32 s0, s1, s0
	v_readlane_b32 s1, v255, 1
	v_fma_f32 v1, -v3, v5, v1
	s_addc_u32 s1, s1, 0
	v_div_fmas_f32 v1, v1, v4, v5
	v_lshl_add_u64 v[4:5], s[0:1], 0, v[160:161]
	v_lshlrev_b64 v[6:7], 10, v[130:131]
	v_pk_mul_f32 v[8:9], v[48:49], v[2:3] op_sel_hi:[1,0]
	v_pk_mul_f32 v[10:11], v[50:51], v[2:3] op_sel_hi:[1,0]
	v_lshl_add_u64 v[6:7], v[4:5], 0, v[6:7]
	v_cvt_pk_bf16_f32 v8, v8, v9
	v_cvt_pk_bf16_f32 v9, v10, v11
	global_store_dwordx2 v[6:7], v[8:9], off
	v_pk_mul_f32 v[8:9], v[76:77], v[2:3] op_sel_hi:[1,0]
	v_pk_mul_f32 v[10:11], v[78:79], v[2:3] op_sel_hi:[1,0]
	v_cvt_pk_bf16_f32 v8, v8, v9
	v_cvt_pk_bf16_f32 v9, v10, v11
	global_store_dwordx2 v[6:7], v[8:9], off offset:32
	v_pk_mul_f32 v[8:9], v[84:85], v[2:3] op_sel_hi:[1,0]
	v_pk_mul_f32 v[10:11], v[86:87], v[2:3] op_sel_hi:[1,0]
	v_cvt_pk_bf16_f32 v8, v8, v9
	v_cvt_pk_bf16_f32 v9, v10, v11
	v_div_fixup_f32 v1, v1, v0, 1.0
	v_cmp_lt_f32_e32 vcc, 0, v0
	global_store_dwordx2 v[6:7], v[8:9], off offset:64
	v_pk_mul_f32 v[8:9], v[92:93], v[2:3] op_sel_hi:[1,0]
	v_pk_mul_f32 v[2:3], v[94:95], v[2:3] op_sel_hi:[1,0]
	v_cndmask_b32_e32 v0, 0, v1, vcc
	v_cvt_pk_bf16_f32 v8, v8, v9
	v_cvt_pk_bf16_f32 v9, v2, v3
	v_lshlrev_b64 v[2:3], 10, v[128:129]
	global_store_dwordx2 v[6:7], v[8:9], off offset:96
	v_lshl_add_u64 v[2:3], v[4:5], 0, v[2:3]
	v_pk_mul_f32 v[4:5], v[40:41], v[0:1] op_sel_hi:[1,0]
	v_pk_mul_f32 v[6:7], v[42:43], v[0:1] op_sel_hi:[1,0]
	v_cvt_pk_bf16_f32 v4, v4, v5
	v_cvt_pk_bf16_f32 v5, v6, v7
	global_store_dwordx2 v[2:3], v[4:5], off
	v_pk_mul_f32 v[4:5], v[72:73], v[0:1] op_sel_hi:[1,0]
	v_pk_mul_f32 v[6:7], v[74:75], v[0:1] op_sel_hi:[1,0]
	v_cvt_pk_bf16_f32 v4, v4, v5
	v_cvt_pk_bf16_f32 v5, v6, v7
	global_store_dwordx2 v[2:3], v[4:5], off offset:32
	v_pk_mul_f32 v[4:5], v[80:81], v[0:1] op_sel_hi:[1,0]
	v_pk_mul_f32 v[6:7], v[82:83], v[0:1] op_sel_hi:[1,0]
	v_cvt_pk_bf16_f32 v4, v4, v5
	v_cvt_pk_bf16_f32 v5, v6, v7
	global_store_dwordx2 v[2:3], v[4:5], off offset:64
	v_pk_mul_f32 v[4:5], v[88:89], v[0:1] op_sel_hi:[1,0]
	v_pk_mul_f32 v[0:1], v[90:91], v[0:1] op_sel_hi:[1,0]
	v_cvt_pk_bf16_f32 v4, v4, v5
	v_cvt_pk_bf16_f32 v5, v0, v1
	global_store_dwordx2 v[2:3], v[4:5], off offset:96
.LBB0_1893:
	v_readlane_b32 s0, v254, 15
	v_readlane_b32 s2, v251, 47
	s_nop 1
	s_cmp_lt_u32 s2, 0x400
	s_cselect_b32 s2, 1, -1
	s_cmpk_lg_i32 s90, 0x200
	s_cselect_b32 s2, 1, s2
	s_mul_i32 s0, s0, s2
	s_mul_i32 s3, s90, s2
	s_add_i32 s40, s40, s0
	v_readlane_b32 s0, v254, 12
	v_readlane_b32 s1, v254, 13
	s_add_i32 s41, s41, s3
	s_nop 0
	s_xor_b64 s[96:97], s[96:97], s[0:1]
	s_add_i32 s81, s81, s3
	s_add_i32 s80, s80, s3
	s_cmpk_gt_u32 s41, 0xbff
	s_cbranch_scc1 .LBB0_2023
